# v92 + last layer's out-proj -> norm -> SwiGLU -> FFN-down as XCD-local barrier chain, final grid sync dropped
# speedup vs baseline: 1.0045x; 1.0045x over previous
; DI const float* in_ptr(const Args& AR, int i) { asm volatile("" : "+s"(i)); return GLOBAL_PTR(const float, AR.in[i]); }
; DI void grid_barrier(unsigned* cnt, unsigned target) {
;     asm volatile("s_waitcnt vmcnt(0) lgkmcnt(0)" ::: "memory");
;     __syncthreads();
;     if (threadIdx.x == 0) {
;         __builtin_amdgcn_fence(__ATOMIC_RELEASE, "agent");
;         asm volatile("s_waitcnt vmcnt(0)" ::: "memory");
;         __hip_atomic_fetch_add(cnt, 1u, __ATOMIC_RELAXED, __HIP_MEMORY_SCOPE_AGENT);
;         while (__hip_atomic_load(cnt, __ATOMIC_RELAXED, __HIP_MEMORY_SCOPE_AGENT) < target) __builtin_amdgcn_s_sleep(2);
;         __builtin_amdgcn_fence(__ATOMIC_ACQUIRE, "agent");
;         asm volatile("s_waitcnt vmcnt(0)" ::: "memory");
;     }
;     __syncthreads();
; }
; __global__ void __launch_bounds__(512, 2) fwd_megakernel(Args args) {
;     ...
;             if (type == T_NORM) {
;                 const int sub = op == 0 ? 0 : (op == 3 ? 1 : 2);
;                 if (even && op == 3) norm_pair_phase(F, srcL, srcC, in_ptr(AR, 4) + (size_t)(l * 3 + sub) * DM, modl, sub);
;                 else norm_phase(F, srcL, srcC, in_ptr(AR, 4) + (size_t)(l * 3 + sub) * DM, modl, sub);
.Lnp_not6:
	s_cmp_eq_u32 s98, 2
	s_cbranch_scc0 .Lnp_nosplit
	s_and_b32 s99, s12, 31
	s_lshr_b32 s8, s12, 5
	s_cmp_lt_u32 s99, 8
	s_cbranch_scc0 .Lnp_classB
	s_mov_b64 s[18:19], exec
	v_readlane_b32 s30, v255, 3
	v_readlane_b32 s31, v255, 4
	s_and_b64 s[30:31], s[18:19], s[30:31]
	s_mov_b64 exec, s[30:31]
	s_cbranch_execz .Lnp_wdone_a
	s_lshl_b32 s9, s100, 3
	s_lshr_b32 s30, s12, 5
	s_lshl_b32 s30, s30, 2
	s_add_u32 s30, s14, s30
	s_addc_u32 s31, s15, 0
